# attention units: 6 per wave on the three-gate-tile workgroups, 4 on the two-gate-tile ones (was 5 / 6)
# speedup vs baseline: 1.0006x; 1.0004x over previous
; __device__ __forceinline__ void attn_mfma(const Args& a, int u0, int ucnt, int ustride) {
;     ...
;     const int lane = threadIdx.x & 63, r32 = lane & 31, hi = lane >> 5;
;     const int kap = 16 * (r32 >> 4) + 8 * ((r32 >> 2) & 1) + 4 * ((r32 >> 3) & 1) + (r32 & 3);
;     for (int uk = 0; uk < ucnt; ++uk) { const int u = u0 + uk * ustride;
;         const int qb = u & 63, bh = u >> 6, h = bh & 15, b = bh >> 4;
;         const size_t rowq = (size_t)b * SEQ + 32 * qb + r32;
;         bf16* qp = QS + rowq * 2048 + 1024 + 64 * h;
;         const bf16* kbase = SK + ((size_t)b * SEQ + kap) * 1024 + 64 * h + 8 * hi;
;         const bf16* vbase = VT + ((size_t)bh * 64 + r32) * 2048 + 8 * hi;
; __global__ void __launch_bounds__(NTHREADS, 2) hybrid_fwd(Args args) {
;     ...
;             if ((int)blockIdx.x < 64) { hgrn_v2(args, lds, (int)blockIdx.x, 64); p0_prologue<1>(args, lds, wave, lane, 2048 + 512 + (int)blockIdx.x * NWAVES + wave, 1024); S.l0 = -1; S.l1 = -1; S.l2 = -1; }
;             else { const int idx = (int)blockIdx.x - 64;
;                 if (idx < 128) attn_mfma(args, idx * 40 + wave, 5, NWAVES); else attn_mfma(args, 5120 + (idx - 128) * 48 + wave, 6, NWAVES);
.LBB0_396:
	s_and_b64 vcc, exec, s[0:1]
	s_cbranch_vccz .LBB0_722
	s_cmp_gt_i32 s33, 63
	s_cbranch_scc0 .LBB0_406
	s_cmpk_lt_u32 s33, 0xc0
	s_cselect_b64 s[38:39], -1, 0
	s_cmpk_gt_u32 s33, 0xbf
	s_cselect_b64 s[0:1], -1, 0
	s_mov_b64 s[2:3], -1
	s_and_b64 vcc, exec, s[0:1]
	s_mul_i32 s2, s33, 48
	v_readlane_b32 s3, v254, 11
	s_add_i32 s44, s2, s3
	s_waitcnt vmcnt(0)
	v_lshlrev_b32_e32 v1, 1, v188
	v_lshrrev_b32_e32 v2, 1, v188
	v_and_b32_e32 v82, 31, v188
	v_readlane_b32 s2, v254, 22
	v_and_b32_e32 v0, 19, v188
	v_and_b32_e32 v1, 8, v1
	v_and_b32_e32 v2, 4, v2
	v_bfe_u32 v3, v188, 5, 1
	v_mov_b32_e32 v85, 0
	v_lshlrev_b32_e32 v84, 12, v82
	v_readlane_b32 s3, v254, 23
	v_or3_b32 v80, v1, v0, v2
	v_lshlrev_b32_e32 v2, 3, v3
	v_lshl_add_u64 v[0:1], s[2:3], 0, v[84:85]
	v_lshlrev_b32_e32 v84, 4, v3
	v_lshl_add_u64 v[86:87], v[0:1], 0, v[84:85]
	v_or_b32_e32 v0, 1, v2
	v_cmp_lt_u32_e64 s[4:5], v0, v82
	v_or_b32_e32 v0, 3, v2
	v_cmp_lt_u32_e64 s[6:7], v0, v82
	v_or_b32_e32 v0, 5, v2
	v_cmp_lt_u32_e64 s[10:11], v0, v82
	v_or_b32_e32 v0, 6, v2
	v_cmp_lt_u32_e64 s[14:15], v0, v82
	v_or_b32_e32 v0, 7, v2
	v_cmp_lt_u32_e64 s[16:17], v0, v82
	v_or_b32_e32 v0, 17, v2
	v_cmp_lt_u32_e64 s[18:19], v0, v82
	v_or_b32_e32 v0, 19, v2
	v_cmp_lt_u32_e64 s[22:23], v0, v82
	v_or_b32_e32 v0, 21, v2
	v_or_b32_e32 v1, 2, v2
	v_cmp_lt_u32_e64 s[26:27], v0, v82
	v_or_b32_e32 v0, 22, v2
	v_cmp_lt_u32_e64 s[8:9], v1, v82
	v_or_b32_e32 v1, 4, v2
	v_cmp_lt_u32_e64 s[30:31], v0, v82
	v_or_b32_e32 v0, 23, v2
	v_cmp_lt_u32_e64 s[12:13], v1, v82
	v_or_b32_e32 v1, 16, v2
	v_cmp_lt_u32_e64 s[34:35], v0, v82
	v_mbcnt_lo_u32_b32 v0, -1, 0
	v_cmp_lt_u32_e64 s[20:21], v1, v82
	v_or_b32_e32 v1, 18, v2
	v_mbcnt_hi_u32_b32 v0, -1, v0
	v_cmp_lt_u32_e64 s[24:25], v1, v82
	v_or_b32_e32 v1, 20, v2
	v_and_b32_e32 v4, 64, v0
	v_cmp_lt_u32_e64 s[28:29], v1, v82
	v_xor_b32_e32 v1, 32, v0
	v_add_u32_e32 v4, 64, v4
	v_cmp_lt_i32_e32 vcc, v1, v4
	s_addk_i32 s44, 0xf000
	v_cmp_lt_u32_e64 s[2:3], v2, v82
	v_cndmask_b32_e32 v0, v0, v1, vcc
	v_lshlrev_b32_e32 v81, 2, v0
	v_lshlrev_b32_e32 v0, 2, v3
	s_mov_b32 s41, 0
	v_cmp_eq_u32_e64 s[36:37], 0, v3
	v_lshlrev_b32_e32 v88, 1, v2
	v_mov_b32_e32 v89, v85
	s_mov_b32 s45, 0x8000
	v_lshlrev_b32_e32 v84, 1, v0
	s_mov_b32 s46, 0
	v_mbcnt_lo_u32_b32 v189, -1, 0
	v_mbcnt_hi_u32_b32 v189, -1, v189
	v_readlane_b32 s78, v254, 11
	v_readlane_b32 s92, v254, 22
	v_readlane_b32 s93, v254, 23
	s_nop 0
	s_lshl_b32 s78, s78, 14
	v_lshrrev_b32_e32 v206, 3, v189
	v_and_b32_e32 v207, 7, v189
	v_lshrrev_b32_e32 v208, 1, v206
	v_xor_b32_e32 v209, v207, v208
	v_xor_b32_e32 v210, 4, v209
	v_lshlrev_b32_e32 v209, 4, v209
	v_lshlrev_b32_e32 v210, 4, v210
	v_lshl_add_u32 v190, v206, 11, v209
	v_lshl_add_u32 v191, v206, 11, v210
	v_add_u32_e32 v191, 0x3c00, v191
	v_add_u32_e32 v192, 0x7800, v190
	v_add_u32_e32 v193, 0x7800, v191
	v_lshrrev_b32_e32 v206, 2, v189
	v_and_b32_e32 v207, 3, v189
	v_bfe_u32 v208, v189, 4, 2
	v_xor_b32_e32 v207, v207, v208
	v_lshlrev_b32_e32 v207, 4, v207
	v_lshl_add_u32 v194, v206, 12, v207
	v_add_u32_e32 v195, 0xfc00, v194
	v_add_u32_e32 v196, 0x1f800, v194
	v_add_u32_e32 v197, 0x2f400, v194
	v_lshrrev_b32_e32 v206, 5, v189
	v_bfe_u32 v207, v80, 1, 3
	v_xor_b32_e32 v207, v207, v206
	v_lshlrev_b32_e32 v208, 3, v80
	v_or_b32_e32 v209, v208, v207
	v_lshl_add_u32 v198, v209, 4, s78
	v_xor_b32_e32 v210, 2, v207
	v_or_b32_e32 v210, v208, v210
	v_lshl_add_u32 v199, v210, 4, s78
	v_xor_b32_e32 v210, 4, v207
	v_or_b32_e32 v210, v208, v210
	v_lshl_add_u32 v200, v210, 4, s78
	v_xor_b32_e32 v210, 6, v207
	v_or_b32_e32 v210, v208, v210
	v_lshl_add_u32 v201, v210, 4, s78
	v_bfe_u32 v207, v82, 2, 2
	v_xor_b32_e32 v207, v207, v206
	v_lshlrev_b32_e32 v208, 2, v82
	v_or_b32_e32 v209, v208, v207
	v_lshl_add_u32 v202, v209, 4, s78
	v_add_u32_e32 v202, 0x1000, v202
	v_xor_b32_e32 v210, 2, v207
	v_or_b32_e32 v210, v208, v210
	v_lshl_add_u32 v203, v210, 4, s78
	v_add_u32_e32 v203, 0x1000, v203
	v_add_u32_e32 v204, 0x800, v202
	v_add_u32_e32 v205, 0x800, v203
	v_readlane_b32 s100, v254, 11
	s_mul_i32 s44, s33, 32
	s_add_i32 s44, s44, 0x0
	s_mov_b32 s101, 4
	s_cmpk_gt_u32 s33, 0xbf
	s_cbranch_scc1 .Latt_cls
	s_mul_i32 s44, s33, 48
	s_add_i32 s44, s44, 0xfffff400
	s_mov_b32 s101, 6
.Latt_cls:
	s_add_i32 s44, s44, s100
	s_branch .LBB0_401
